# barrier: cross-XCD arrival counter removed; each XCD leader (after its L2 writeback) adds 1 to every XCC generation counter, all workgroups poll their XCC counter until it reaches (round+1)*populated
# speedup vs baseline: 1.0016x; 1.0016x over previous
.LBB0_856:
	s_or_b64 exec, exec, s[2:3]
	v_cvt_f32_u32_e32 v5, v3
	s_waitcnt vmcnt(0)
	v_readfirstlane_b32 s2, v4
	v_sub_u32_e32 v4, 0, v3
	v_rcp_iflag_f32_e32 v5, v5
	v_add_u32_e32 v6, s2, v0
	v_mul_f32_e32 v5, 0x4f7ffffe, v5
	v_cvt_u32_f32_e32 v5, v5
	v_mul_lo_u32 v0, v4, v5
	v_mul_hi_u32 v0, v5, v0
	v_add_u32_e32 v0, v5, v0
	v_mul_hi_u32 v0, v6, v0
	v_mul_lo_u32 v4, v0, v3
	v_sub_u32_e32 v4, v6, v4
	v_add_u32_e32 v5, 1, v0
	v_cmp_ge_u32_e32 vcc, v4, v3
	s_nop 1
	v_cndmask_b32_e32 v0, v0, v5, vcc
	v_sub_u32_e32 v5, v4, v3
	v_cndmask_b32_e32 v4, v4, v5, vcc
	v_add_u32_e32 v5, 1, v0
	v_cmp_ge_u32_e32 vcc, v4, v3
	v_add_u32_e32 v4, 1, v6
	s_nop 0
	v_cndmask_b32_e32 v0, v0, v5, vcc
	v_mul_lo_u32 v5, v3, v0
	v_add_u32_e32 v3, v5, v3
	v_cmp_ne_u32_e32 vcc, v4, v3
	s_cbranch_vccnz .Lxb_poll
	buffer_wbl2 sc1
	v_readlane_b32 s6, v251, 54
	v_readlane_b32 s7, v251, 55
	s_waitcnt vmcnt(0)
	s_add_u32 s6, s6, 0x2200
	s_addc_u32 s7, s7, 0
	v_mov_b64_e32 v[4:5], s[6:7]
	global_atomic_add v[4:5], v228, off
	global_atomic_add v[4:5], v228, off offset:256
	global_atomic_add v[4:5], v228, off offset:512
	global_atomic_add v[4:5], v228, off offset:768
	global_atomic_add v[4:5], v228, off offset:1024
	global_atomic_add v[4:5], v228, off offset:1280
	global_atomic_add v[4:5], v228, off offset:1536
	global_atomic_add v[4:5], v228, off offset:1792
	global_atomic_add v[4:5], v228, off offset:2048
	global_atomic_add v[4:5], v228, off offset:2304
	global_atomic_add v[4:5], v228, off offset:2560
	global_atomic_add v[4:5], v228, off offset:2816
	global_atomic_add v[4:5], v228, off offset:3072
	global_atomic_add v[4:5], v228, off offset:3328
	global_atomic_add v[4:5], v228, off offset:3584
	global_atomic_add v[4:5], v228, off offset:3840
.Lxb_poll:
	s_waitcnt lgkmcnt(0)
	v_add_u32_e32 v0, 1, v0
	v_mul_lo_u32 v0, v0, v2
	s_mov_b64 vcc, exec
	s_and_saveexec_b64 s[2:3], vcc
	s_xor_b64 s[2:3], exec, s[2:3]
	s_cbranch_execz .LBB0_870
	v_readlane_b32 s6, v252, 58
	v_readlane_b32 s7, v252, 59
	s_waitcnt lgkmcnt(0)
	s_nop 3
	global_load_dword v2, v1, s[6:7] sc1
	s_waitcnt vmcnt(0)
	v_cmp_lt_u32_e32 vcc, v2, v0
	s_and_saveexec_b64 s[6:7], vcc
	s_cbranch_execz .LBB0_869
	s_mov_b32 s5, 1
	s_mov_b64 s[8:9], 0
	s_branch .LBB0_860

.LBB0_862:
	v_readlane_b32 s12, v252, 58
	v_readlane_b32 s13, v252, 59
	s_add_i32 s5, s5, 1
	s_mov_b64 s[14:15], -1
	s_nop 2
	global_load_dword v2, v1, s[12:13] sc1
	s_waitcnt vmcnt(0)
	v_cmp_ge_u32_e32 vcc, v2, v0
	s_orn2_b64 s[12:13], vcc, exec
	s_branch .LBB0_859

.LBB0_870:
	s_andn2_saveexec_b64 s[2:3], s[2:3]
	s_getpc_b64 s[98:99]
